# adds P14 epilogue residual-load prefetch (5 sub-steps ahead into spare fragment registers, counted vmcnt)
# baseline (speedup 1.0000x reference)
; __device__ __forceinline__ unsigned pk2(float lo, float hi) { return pg8::cvt_pk_bf16(lo, hi); }
;     __device__ __forceinline__ void operator()(AccRef acc, const pg8::Unit& u, int wr, int wc, int fr, int fq) const {
;     ...
;             for (int m = 0; m < 4; ++m) {
;                 const int row = u.pm * 256 + ai * 128 + wr * 64 + m * 16 + fr;
;                 float sq = 0.f;
; #pragma unroll
;                 for (int bj = 0; bj < 2; ++bj) {
;                     const size_t off = (size_t)row * DM + col0 + bj * 128;
;                     f32x4 b0, b1;
;                     if (BASE_BF16) { const u32x4 bb = *(const u32x4*)((const bf16_t*)base + off);
;                         b0 = (f32x4){__uint_as_float(bb.x << 16), __uint_as_float(bb.x & 0xffff0000u), __uint_as_float(bb.y << 16), __uint_as_float(bb.y & 0xffff0000u)};
;                         b1 = (f32x4){__uint_as_float(bb.z << 16), __uint_as_float(bb.z & 0xffff0000u), __uint_as_float(bb.w << 16), __uint_as_float(bb.w & 0xffff0000u)}; }
;                     else { b0 = *(const f32x4*)((const float*)base + off); b1 = *(const f32x4*)((const float*)base + off + 4); }
;                     const f32x4 o0 = b0 + acc[ai][bj][m][0] * coef, o1 = b1 + acc[ai][bj][m][1] * coef;
;                     if (OUT_BF16) { u32x4 w; w.x = pk2(o0[0], o0[1]); w.y = pk2(o0[2], o0[3]); w.z = pk2(o1[0], o1[1]); w.w = pk2(o1[2], o1[3]); *(u32x4*)((bf16_t*)out + off) = w; }
;                     else { *(f32x4*)((float*)out + off) = o0; *(f32x4*)((float*)out + off + 4) = o1; }
;                     sq += (o0[0] * o0[0] + o0[1] * o0[1]) + (o0[2] * o0[2] + o0[3] * o0[3]) + (o1[0] * o1[0] + o1[1] * o1[1]) + (o1[2] * o1[2] + o1[3] * o1[3]);
.LBB0_895:
	v_lshl_add_u32 v18, s52, 8, v156
	v_lshl_or_b32 v16, s53, 8, v158
	v_ashrrev_i32_e32 v19, 31, v18
	v_ashrrev_i32_e32 v17, 31, v16
	v_lshlrev_b64 v[24:25], 10, v[18:19]
	v_lshl_add_u64 v[24:25], v[24:25], 0, v[16:17]
	v_lshlrev_b64 v[40:41], 1, v[24:25]
	v_mov_b32_e32 v193, v40
	s_waitcnt lgkmcnt(0)
	v_lshl_add_u64 v[42:43], s[10:11], 0, v[40:41]
	s_nop 0
	v_mov_b32_e32 v192, v193
	global_load_dwordx4 v[168:171], v192, s[10:11]
	v_mov_b32_e32 v192, v193
	global_load_dwordx4 v[172:175], v192, s[10:11] offset:256
	v_add_u32_e32 v192, 0x8000, v193
	global_load_dwordx4 v[176:179], v192, s[10:11]
	v_add_u32_e32 v192, 0x8000, v193
	global_load_dwordx4 v[180:183], v192, s[10:11] offset:256
	v_add_u32_e32 v192, 0x10000, v193
	global_load_dwordx4 v[184:187], v192, s[10:11]
	v_lshl_add_u64 v[162:163], s[14:15], 0, v[40:41]
	v_or_b32_e32 v40, 0x100, v40
	v_lshl_add_u64 v[40:41], s[14:15], 0, v[40:41]
	s_and_b64 vcc, exec, s[6:7]
	s_mov_b64 s[6:7], -1
	s_waitcnt vmcnt(4)
	v_lshlrev_b32_e32 v164, 16, v168
	v_and_b32_e32 v165, 0xffff0000, v168
	v_lshlrev_b32_e32 v24, 16, v169
	v_and_b32_e32 v25, 0xffff0000, v169
	v_lshlrev_b32_e32 v166, 16, v170
	v_and_b32_e32 v167, 0xffff0000, v170
	v_lshlrev_b32_e32 v26, 16, v171
	v_and_b32_e32 v27, 0xffff0000, v171
	v_add_u32_e32 v192, 0x10000, v193
	global_load_dwordx4 v[188:191], v192, s[10:11] offset:256
	v_pk_add_f32 v[148:149], v[148:149], v[24:25]
	v_pk_add_f32 v[24:25], v[150:151], v[164:165]
	v_pk_add_f32 v[150:151], v[152:153], v[26:27]
	v_pk_add_f32 v[26:27], v[154:155], v[166:167]
	v_cvt_pk_bf16_f32 v24, v24, v25
	v_cvt_pk_bf16_f32 v25, v148, v149
	s_nop 0
	v_cvt_pk_bf16_f32 v26, v26, v27
	v_cvt_pk_bf16_f32 v27, v150, v151
	global_store_dwordx4 v[162:163], v[24:27], off
	s_nop 0
	v_or_b32_e32 v42, 16, v18
	v_ashrrev_i32_e32 v43, 31, v42
	v_lshlrev_b64 v[42:43], 10, v[42:43]
	v_lshl_add_u64 v[42:43], v[42:43], 0, v[16:17]
	v_lshlrev_b64 v[42:43], 1, v[42:43]
	v_lshl_add_u64 v[148:149], s[10:11], 0, v[42:43]
	s_waitcnt vmcnt(5)
	v_lshlrev_b32_e32 v150, 16, v172
	v_and_b32_e32 v151, 0xffff0000, v172
	v_lshlrev_b32_e32 v24, 16, v173
	v_and_b32_e32 v25, 0xffff0000, v173
	v_lshlrev_b32_e32 v152, 16, v174
	v_and_b32_e32 v153, 0xffff0000, v174
	v_lshlrev_b32_e32 v26, 16, v175
	v_and_b32_e32 v27, 0xffff0000, v175
	v_add_u32_e32 v192, 0x18000, v193
	global_load_dwordx4 v[168:171], v192, s[10:11]
	v_pk_add_f32 v[124:125], v[124:125], v[24:25]
	v_pk_add_f32 v[24:25], v[126:127], v[150:151]
	v_pk_add_f32 v[126:127], v[144:145], v[26:27]
	v_pk_add_f32 v[26:27], v[146:147], v[152:153]
	v_cvt_pk_bf16_f32 v24, v24, v25
	v_cvt_pk_bf16_f32 v25, v124, v125
	s_nop 0
	v_cvt_pk_bf16_f32 v26, v26, v27
	v_cvt_pk_bf16_f32 v27, v126, v127
	global_store_dwordx4 v[40:41], v[24:27], off
	s_nop 0
	v_lshl_add_u64 v[40:41], s[14:15], 0, v[42:43]
	v_or_b32_e32 v42, 0x100, v42
	v_lshl_add_u64 v[42:43], s[14:15], 0, v[42:43]
	s_waitcnt vmcnt(6)
	v_lshlrev_b32_e32 v124, 16, v176
	v_and_b32_e32 v125, 0xffff0000, v176
	v_lshlrev_b32_e32 v24, 16, v177
	v_and_b32_e32 v25, 0xffff0000, v177
	v_lshlrev_b32_e32 v126, 16, v178
	v_and_b32_e32 v127, 0xffff0000, v178
	v_lshlrev_b32_e32 v26, 16, v179
	v_and_b32_e32 v27, 0xffff0000, v179
	v_add_u32_e32 v192, 0x18000, v193
	global_load_dwordx4 v[172:175], v192, s[10:11] offset:256
	v_pk_add_f32 v[118:119], v[118:119], v[24:25]
	v_pk_add_f32 v[24:25], v[116:117], v[124:125]
	v_pk_add_f32 v[116:117], v[120:121], v[26:27]
	v_pk_add_f32 v[26:27], v[122:123], v[126:127]
	v_cvt_pk_bf16_f32 v24, v24, v25
	v_cvt_pk_bf16_f32 v25, v118, v119
	s_nop 0
	v_cvt_pk_bf16_f32 v26, v26, v27
	v_cvt_pk_bf16_f32 v27, v116, v117
	global_store_dwordx4 v[40:41], v[24:27], off
	s_nop 0
	v_or_b32_e32 v40, 32, v18
	v_ashrrev_i32_e32 v41, 31, v40
	v_lshlrev_b64 v[40:41], 10, v[40:41]
	v_lshl_add_u64 v[40:41], v[40:41], 0, v[16:17]
	v_lshlrev_b64 v[40:41], 1, v[40:41]
	v_lshl_add_u64 v[116:117], s[10:11], 0, v[40:41]
	s_waitcnt vmcnt(7)
	v_lshlrev_b32_e32 v118, 16, v180
	v_and_b32_e32 v119, 0xffff0000, v180
	v_lshlrev_b32_e32 v24, 16, v181
	v_and_b32_e32 v25, 0xffff0000, v181
	v_lshlrev_b32_e32 v120, 16, v182
	v_and_b32_e32 v121, 0xffff0000, v182
	v_lshlrev_b32_e32 v26, 16, v183
	v_and_b32_e32 v27, 0xffff0000, v183
	v_add_u32_e32 v192, 0x40000, v193
	global_load_dwordx4 v[176:179], v192, s[10:11]
	v_pk_add_f32 v[108:109], v[108:109], v[24:25]
	v_pk_add_f32 v[24:25], v[110:111], v[118:119]
	v_pk_add_f32 v[110:111], v[112:113], v[26:27]
	v_pk_add_f32 v[26:27], v[114:115], v[120:121]
	v_cvt_pk_bf16_f32 v24, v24, v25
	v_cvt_pk_bf16_f32 v25, v108, v109
	s_nop 0
	v_cvt_pk_bf16_f32 v26, v26, v27
	v_cvt_pk_bf16_f32 v27, v110, v111
	global_store_dwordx4 v[42:43], v[24:27], off
	s_nop 0
	v_lshl_add_u64 v[42:43], s[14:15], 0, v[40:41]
	v_or_b32_e32 v40, 0x100, v40
	v_lshl_add_u64 v[40:41], s[14:15], 0, v[40:41]
	s_waitcnt vmcnt(8)
	v_lshlrev_b32_e32 v108, 16, v184
	v_and_b32_e32 v109, 0xffff0000, v184
	v_lshlrev_b32_e32 v24, 16, v185
	v_and_b32_e32 v25, 0xffff0000, v185
	v_lshlrev_b32_e32 v110, 16, v186
	v_and_b32_e32 v111, 0xffff0000, v186
	v_lshlrev_b32_e32 v26, 16, v187
	v_and_b32_e32 v27, 0xffff0000, v187
	v_add_u32_e32 v192, 0x40000, v193
	global_load_dwordx4 v[180:183], v192, s[10:11] offset:256
	v_pk_add_f32 v[100:101], v[100:101], v[24:25]
	v_pk_add_f32 v[24:25], v[102:103], v[108:109]
	v_pk_add_f32 v[102:103], v[104:105], v[26:27]
	v_pk_add_f32 v[26:27], v[106:107], v[110:111]
	v_cvt_pk_bf16_f32 v24, v24, v25
	v_cvt_pk_bf16_f32 v25, v100, v101
	s_nop 0
	v_cvt_pk_bf16_f32 v26, v26, v27
	v_cvt_pk_bf16_f32 v27, v102, v103
	global_store_dwordx4 v[42:43], v[24:27], off
	s_nop 0
	v_or_b32_e32 v42, 48, v18
	v_ashrrev_i32_e32 v43, 31, v42
	v_lshlrev_b64 v[42:43], 10, v[42:43]
	v_lshl_add_u64 v[42:43], v[42:43], 0, v[16:17]
	v_lshlrev_b64 v[42:43], 1, v[42:43]
	v_lshl_add_u64 v[100:101], s[10:11], 0, v[42:43]
	s_waitcnt vmcnt(9)
; __device__ __forceinline__ unsigned pk2(float lo, float hi) { return pg8::cvt_pk_bf16(lo, hi); }
;     __device__ __forceinline__ void operator()(AccRef acc, const pg8::Unit& u, int wr, int wc, int fr, int fq) const {
;     ...
;             for (int m = 0; m < 4; ++m) {
;                 const int row = u.pm * 256 + ai * 128 + wr * 64 + m * 16 + fr;
;                 float sq = 0.f;
; #pragma unroll
;                 for (int bj = 0; bj < 2; ++bj) {
;                     const size_t off = (size_t)row * DM + col0 + bj * 128;
;                     f32x4 b0, b1;
;                     if (BASE_BF16) { const u32x4 bb = *(const u32x4*)((const bf16_t*)base + off);
;                         b0 = (f32x4){__uint_as_float(bb.x << 16), __uint_as_float(bb.x & 0xffff0000u), __uint_as_float(bb.y << 16), __uint_as_float(bb.y & 0xffff0000u)};
;                         b1 = (f32x4){__uint_as_float(bb.z << 16), __uint_as_float(bb.z & 0xffff0000u), __uint_as_float(bb.w << 16), __uint_as_float(bb.w & 0xffff0000u)}; }
;                     else { b0 = *(const f32x4*)((const float*)base + off); b1 = *(const f32x4*)((const float*)base + off + 4); }
;                     const f32x4 o0 = b0 + acc[ai][bj][m][0] * coef, o1 = b1 + acc[ai][bj][m][1] * coef;
;                     if (OUT_BF16) { u32x4 w; w.x = pk2(o0[0], o0[1]); w.y = pk2(o0[2], o0[3]); w.z = pk2(o1[0], o1[1]); w.w = pk2(o1[2], o1[3]); *(u32x4*)((bf16_t*)out + off) = w; }
;                     else { *(f32x4*)((float*)out + off) = o0; *(f32x4*)((float*)out + off + 4) = o1; }
;                     sq += (o0[0] * o0[0] + o0[1] * o0[1]) + (o0[2] * o0[2] + o0[3] * o0[3]) + (o1[0] * o1[0] + o1[1] * o1[1]) + (o1[2] * o1[2] + o1[3] * o1[3]);
	v_lshlrev_b32_e32 v102, 16, v188
	v_and_b32_e32 v103, 0xffff0000, v188
	v_lshlrev_b32_e32 v24, 16, v189
	v_and_b32_e32 v25, 0xffff0000, v189
	v_lshlrev_b32_e32 v104, 16, v190
	v_and_b32_e32 v105, 0xffff0000, v190
	v_lshlrev_b32_e32 v26, 16, v191
	v_and_b32_e32 v27, 0xffff0000, v191
	v_add_u32_e32 v192, 0x48000, v193
	global_load_dwordx4 v[184:187], v192, s[10:11]
	v_pk_add_f32 v[92:93], v[92:93], v[24:25]
	v_pk_add_f32 v[24:25], v[94:95], v[102:103]
	v_pk_add_f32 v[94:95], v[96:97], v[26:27]
	v_pk_add_f32 v[26:27], v[98:99], v[104:105]
	v_cvt_pk_bf16_f32 v24, v24, v25
	v_cvt_pk_bf16_f32 v25, v92, v93
	s_nop 0
	v_cvt_pk_bf16_f32 v26, v26, v27
	v_cvt_pk_bf16_f32 v27, v94, v95
	global_store_dwordx4 v[40:41], v[24:27], off
	s_nop 0
	v_lshl_add_u64 v[40:41], s[14:15], 0, v[42:43]
	v_or_b32_e32 v42, 0x100, v42
	v_lshl_add_u64 v[42:43], s[14:15], 0, v[42:43]
	s_waitcnt vmcnt(9)
	v_lshlrev_b32_e32 v92, 16, v168
	v_and_b32_e32 v93, 0xffff0000, v168
	v_lshlrev_b32_e32 v24, 16, v169
	v_and_b32_e32 v25, 0xffff0000, v169
	v_lshlrev_b32_e32 v94, 16, v170
	v_and_b32_e32 v95, 0xffff0000, v170
	v_lshlrev_b32_e32 v26, 16, v171
	v_and_b32_e32 v27, 0xffff0000, v171
	v_add_u32_e32 v192, 0x48000, v193
	global_load_dwordx4 v[188:191], v192, s[10:11] offset:256
	v_pk_add_f32 v[84:85], v[84:85], v[24:25]
	v_pk_add_f32 v[24:25], v[86:87], v[92:93]
	v_pk_add_f32 v[86:87], v[88:89], v[26:27]
	v_pk_add_f32 v[26:27], v[90:91], v[94:95]
	v_cvt_pk_bf16_f32 v24, v24, v25
	v_cvt_pk_bf16_f32 v25, v84, v85
	s_nop 0
	v_cvt_pk_bf16_f32 v26, v26, v27
	v_cvt_pk_bf16_f32 v27, v86, v87
	global_store_dwordx4 v[40:41], v[24:27], off
	s_nop 0
	v_add_u32_e32 v40, 0x80, v18
	v_ashrrev_i32_e32 v41, 31, v40
	v_lshlrev_b64 v[40:41], 10, v[40:41]
	v_lshl_add_u64 v[40:41], v[40:41], 0, v[16:17]
	v_lshlrev_b64 v[40:41], 1, v[40:41]
	v_lshl_add_u64 v[84:85], s[10:11], 0, v[40:41]
	s_waitcnt vmcnt(9)
	v_lshlrev_b32_e32 v86, 16, v172
	v_and_b32_e32 v87, 0xffff0000, v172
	v_lshlrev_b32_e32 v24, 16, v173
	v_and_b32_e32 v25, 0xffff0000, v173
	v_lshlrev_b32_e32 v88, 16, v174
	v_and_b32_e32 v89, 0xffff0000, v174
	v_lshlrev_b32_e32 v26, 16, v175
	v_and_b32_e32 v27, 0xffff0000, v175
	v_add_u32_e32 v192, 0x50000, v193
	global_load_dwordx4 v[168:171], v192, s[10:11]
	v_pk_add_f32 v[76:77], v[76:77], v[24:25]
	v_pk_add_f32 v[24:25], v[78:79], v[86:87]
	v_pk_add_f32 v[78:79], v[80:81], v[26:27]
	v_pk_add_f32 v[26:27], v[82:83], v[88:89]
	v_cvt_pk_bf16_f32 v24, v24, v25
	v_cvt_pk_bf16_f32 v25, v76, v77
	s_nop 0
	v_cvt_pk_bf16_f32 v26, v26, v27
	v_cvt_pk_bf16_f32 v27, v78, v79
	global_store_dwordx4 v[42:43], v[24:27], off
	s_nop 0
	v_lshl_add_u64 v[42:43], s[14:15], 0, v[40:41]
	v_or_b32_e32 v40, 0x100, v40
	v_lshl_add_u64 v[40:41], s[14:15], 0, v[40:41]
	s_waitcnt vmcnt(9)
	v_lshlrev_b32_e32 v76, 16, v176
	v_and_b32_e32 v77, 0xffff0000, v176
	v_lshlrev_b32_e32 v24, 16, v177
	v_and_b32_e32 v25, 0xffff0000, v177
	v_lshlrev_b32_e32 v78, 16, v178
	v_and_b32_e32 v79, 0xffff0000, v178
	v_lshlrev_b32_e32 v26, 16, v179
	v_and_b32_e32 v27, 0xffff0000, v179
	v_add_u32_e32 v192, 0x50000, v193
	global_load_dwordx4 v[172:175], v192, s[10:11] offset:256
	v_pk_add_f32 v[68:69], v[68:69], v[24:25]
	v_pk_add_f32 v[24:25], v[70:71], v[76:77]
	v_pk_add_f32 v[70:71], v[72:73], v[26:27]
	v_pk_add_f32 v[26:27], v[74:75], v[78:79]
	v_cvt_pk_bf16_f32 v24, v24, v25
	v_cvt_pk_bf16_f32 v25, v68, v69
	s_nop 0
	v_cvt_pk_bf16_f32 v26, v26, v27
	v_cvt_pk_bf16_f32 v27, v70, v71
	global_store_dwordx4 v[42:43], v[24:27], off
	s_nop 0
	v_add_u32_e32 v42, 0x90, v18
	v_ashrrev_i32_e32 v43, 31, v42
	v_lshlrev_b64 v[42:43], 10, v[42:43]
	v_lshl_add_u64 v[42:43], v[42:43], 0, v[16:17]
	v_lshlrev_b64 v[42:43], 1, v[42:43]
	v_lshl_add_u64 v[68:69], s[10:11], 0, v[42:43]
	s_waitcnt vmcnt(9)
	v_lshlrev_b32_e32 v70, 16, v180
	v_and_b32_e32 v71, 0xffff0000, v180
	v_lshlrev_b32_e32 v24, 16, v181
	v_and_b32_e32 v25, 0xffff0000, v181
	v_lshlrev_b32_e32 v72, 16, v182
	v_and_b32_e32 v73, 0xffff0000, v182
	v_lshlrev_b32_e32 v26, 16, v183
	v_and_b32_e32 v27, 0xffff0000, v183
	v_add_u32_e32 v192, 0x58000, v193
	global_load_dwordx4 v[176:179], v192, s[10:11]
	v_pk_add_f32 v[60:61], v[60:61], v[24:25]
	v_pk_add_f32 v[24:25], v[62:63], v[70:71]
	v_pk_add_f32 v[62:63], v[64:65], v[26:27]
	v_pk_add_f32 v[26:27], v[66:67], v[72:73]
	v_cvt_pk_bf16_f32 v24, v24, v25
	v_cvt_pk_bf16_f32 v25, v60, v61
	s_nop 0
	v_cvt_pk_bf16_f32 v26, v26, v27
	v_cvt_pk_bf16_f32 v27, v62, v63
	global_store_dwordx4 v[40:41], v[24:27], off
	s_nop 0
	v_lshl_add_u64 v[40:41], s[14:15], 0, v[42:43]
	v_or_b32_e32 v42, 0x100, v42
	v_lshl_add_u64 v[42:43], s[14:15], 0, v[42:43]
	s_waitcnt vmcnt(9)
; __device__ __forceinline__ unsigned pk2(float lo, float hi) { return pg8::cvt_pk_bf16(lo, hi); }
; template <class Epi, class Sched, bool ALIGN_EPI = false, bool SP2 = false>
; __device__ __forceinline__ void gemm_phase(PG8_LAS unsigned char* lds, const Gemm g, const Sched& S, const Epi& E) {
;     ...
;         if constexpr (!Epi::AFTER_DRAIN) { E(acc, cur, wr, wc, fr, fq); S.done(cur); }
;         if (!has_next) break;
;     __device__ __forceinline__ void operator()(AccRef acc, const pg8::Unit& u, int wr, int wc, int fr, int fq) const {
;     ...
;             for (int m = 0; m < 4; ++m) {
;                 const int row = u.pm * 256 + ai * 128 + wr * 64 + m * 16 + fr;
;                 float sq = 0.f;
; #pragma unroll
;                 for (int bj = 0; bj < 2; ++bj) {
;                     const size_t off = (size_t)row * DM + col0 + bj * 128;
;                     f32x4 b0, b1;
;                     if (BASE_BF16) { const u32x4 bb = *(const u32x4*)((const bf16_t*)base + off);
;                         b0 = (f32x4){__uint_as_float(bb.x << 16), __uint_as_float(bb.x & 0xffff0000u), __uint_as_float(bb.y << 16), __uint_as_float(bb.y & 0xffff0000u)};
;                         b1 = (f32x4){__uint_as_float(bb.z << 16), __uint_as_float(bb.z & 0xffff0000u), __uint_as_float(bb.w << 16), __uint_as_float(bb.w & 0xffff0000u)}; }
;                     else { b0 = *(const f32x4*)((const float*)base + off); b1 = *(const f32x4*)((const float*)base + off + 4); }
;                     const f32x4 o0 = b0 + acc[ai][bj][m][0] * coef, o1 = b1 + acc[ai][bj][m][1] * coef;
;                     if (OUT_BF16) { u32x4 w; w.x = pk2(o0[0], o0[1]); w.y = pk2(o0[2], o0[3]); w.z = pk2(o1[0], o1[1]); w.w = pk2(o1[2], o1[3]); *(u32x4*)((bf16_t*)out + off) = w; }
;                     else { *(f32x4*)((float*)out + off) = o0; *(f32x4*)((float*)out + off + 4) = o1; }
;                     sq += (o0[0] * o0[0] + o0[1] * o0[1]) + (o0[2] * o0[2] + o0[3] * o0[3]) + (o1[0] * o1[0] + o1[1] * o1[1]) + (o1[2] * o1[2] + o1[3] * o1[3]);
	v_lshlrev_b32_e32 v60, 16, v184
	v_and_b32_e32 v61, 0xffff0000, v184
	v_lshlrev_b32_e32 v24, 16, v185
	v_and_b32_e32 v25, 0xffff0000, v185
	v_lshlrev_b32_e32 v62, 16, v186
	v_and_b32_e32 v63, 0xffff0000, v186
	v_lshlrev_b32_e32 v26, 16, v187
	v_and_b32_e32 v27, 0xffff0000, v187
	v_add_u32_e32 v192, 0x58000, v193
	global_load_dwordx4 v[180:183], v192, s[10:11] offset:256
	v_pk_add_f32 v[54:55], v[54:55], v[24:25]
	v_pk_add_f32 v[24:25], v[52:53], v[60:61]
	v_pk_add_f32 v[52:53], v[56:57], v[26:27]
	v_pk_add_f32 v[26:27], v[58:59], v[62:63]
	v_cvt_pk_bf16_f32 v24, v24, v25
	v_cvt_pk_bf16_f32 v25, v54, v55
	s_nop 0
	v_cvt_pk_bf16_f32 v26, v26, v27
	v_cvt_pk_bf16_f32 v27, v52, v53
	global_store_dwordx4 v[40:41], v[24:27], off
	s_nop 0
	v_add_u32_e32 v40, 0xa0, v18
	v_ashrrev_i32_e32 v41, 31, v40
	v_lshlrev_b64 v[40:41], 10, v[40:41]
	v_lshl_add_u64 v[40:41], v[40:41], 0, v[16:17]
	v_lshlrev_b64 v[40:41], 1, v[40:41]
	v_lshl_add_u64 v[52:53], s[10:11], 0, v[40:41]
	v_add_u32_e32 v18, 0xb0, v18
	v_ashrrev_i32_e32 v19, 31, v18
	v_lshlrev_b64 v[18:19], 10, v[18:19]
	v_lshl_add_u64 v[16:17], v[18:19], 0, v[16:17]
	s_waitcnt vmcnt(9)
	v_lshlrev_b32_e32 v54, 16, v188
	v_and_b32_e32 v55, 0xffff0000, v188
	v_lshlrev_b32_e32 v24, 16, v189
	v_and_b32_e32 v25, 0xffff0000, v189
	v_lshlrev_b32_e32 v56, 16, v190
	v_and_b32_e32 v57, 0xffff0000, v190
	v_lshlrev_b32_e32 v26, 16, v191
	v_and_b32_e32 v27, 0xffff0000, v191
	v_pk_add_f32 v[44:45], v[44:45], v[24:25]
	v_pk_add_f32 v[24:25], v[46:47], v[54:55]
	v_pk_add_f32 v[46:47], v[48:49], v[26:27]
	v_pk_add_f32 v[26:27], v[50:51], v[56:57]
	v_cvt_pk_bf16_f32 v24, v24, v25
	v_cvt_pk_bf16_f32 v25, v44, v45
	s_nop 0
	v_cvt_pk_bf16_f32 v26, v26, v27
	v_cvt_pk_bf16_f32 v27, v46, v47
	global_store_dwordx4 v[42:43], v[24:27], off
	s_nop 0
	v_lshl_add_u64 v[42:43], s[14:15], 0, v[40:41]
	v_or_b32_e32 v40, 0x100, v40
	s_waitcnt vmcnt(8)
	v_lshlrev_b32_e32 v44, 16, v168
	v_and_b32_e32 v45, 0xffff0000, v168
	v_lshlrev_b32_e32 v24, 16, v169
	v_and_b32_e32 v25, 0xffff0000, v169
	v_lshlrev_b32_e32 v46, 16, v170
	v_and_b32_e32 v47, 0xffff0000, v170
	v_lshlrev_b32_e32 v26, 16, v171
	v_and_b32_e32 v27, 0xffff0000, v171
	v_pk_add_f32 v[36:37], v[36:37], v[24:25]
	v_pk_add_f32 v[24:25], v[38:39], v[44:45]
	v_pk_add_f32 v[34:35], v[34:35], v[26:27]
	v_pk_add_f32 v[26:27], v[32:33], v[46:47]
	v_cvt_pk_bf16_f32 v24, v24, v25
	v_cvt_pk_bf16_f32 v25, v36, v37
	v_lshlrev_b64 v[32:33], 1, v[16:17]
	v_cvt_pk_bf16_f32 v26, v26, v27
	v_cvt_pk_bf16_f32 v27, v34, v35
	global_store_dwordx4 v[42:43], v[24:27], off
	s_nop 0
	v_lshl_add_u64 v[36:37], s[14:15], 0, v[40:41]
	v_lshl_add_u64 v[34:35], s[10:11], 0, v[32:33]
	s_waitcnt vmcnt(7)
	v_lshlrev_b32_e32 v16, 16, v172
	v_and_b32_e32 v17, 0xffff0000, v172
	v_lshlrev_b32_e32 v18, 16, v173
	v_and_b32_e32 v19, 0xffff0000, v173
	v_lshlrev_b32_e32 v24, 16, v174
	v_and_b32_e32 v25, 0xffff0000, v174
	v_lshlrev_b32_e32 v26, 16, v175
	v_and_b32_e32 v27, 0xffff0000, v175
	v_pk_add_f32 v[18:19], v[20:21], v[18:19]
	v_pk_add_f32 v[16:17], v[22:23], v[16:17]
	v_pk_add_f32 v[20:21], v[28:29], v[26:27]
	v_pk_add_f32 v[22:23], v[30:31], v[24:25]
	v_cvt_pk_bf16_f32 v16, v16, v17
	v_cvt_pk_bf16_f32 v17, v18, v19
	s_nop 0
	v_cvt_pk_bf16_f32 v18, v22, v23
	v_cvt_pk_bf16_f32 v19, v20, v21
	global_store_dwordx4 v[36:37], v[16:19], off
	s_nop 0
	v_lshl_add_u64 v[20:21], s[14:15], 0, v[32:33]
	v_or_b32_e32 v32, 0x100, v32
	s_waitcnt vmcnt(6)
	v_lshlrev_b32_e32 v22, 16, v176
	v_and_b32_e32 v23, 0xffff0000, v176
	v_lshlrev_b32_e32 v16, 16, v177
	v_and_b32_e32 v17, 0xffff0000, v177
	v_lshlrev_b32_e32 v24, 16, v178
	v_and_b32_e32 v25, 0xffff0000, v178
	v_lshlrev_b32_e32 v18, 16, v179
	v_and_b32_e32 v19, 0xffff0000, v179
	v_pk_add_f32 v[16:17], v[8:9], v[16:17]
	v_pk_add_f32 v[8:9], v[10:11], v[22:23]
	v_pk_add_f32 v[10:11], v[14:15], v[24:25]
	v_pk_add_f32 v[12:13], v[12:13], v[18:19]
	v_cvt_pk_bf16_f32 v8, v8, v9
	v_cvt_pk_bf16_f32 v9, v16, v17
	v_cvt_pk_bf16_f32 v10, v10, v11
	s_nop 0
	v_cvt_pk_bf16_f32 v11, v12, v13
	global_store_dwordx4 v[20:21], v[8:11], off
	s_nop 0
	v_lshl_add_u64 v[12:13], s[14:15], 0, v[32:33]
	s_waitcnt vmcnt(5)
	v_lshlrev_b32_e32 v14, 16, v180
	v_and_b32_e32 v15, 0xffff0000, v180
	v_lshlrev_b32_e32 v8, 16, v181
	v_and_b32_e32 v9, 0xffff0000, v181
	v_lshlrev_b32_e32 v16, 16, v182
	v_and_b32_e32 v17, 0xffff0000, v182
	v_lshlrev_b32_e32 v10, 16, v183
	v_and_b32_e32 v11, 0xffff0000, v183
	v_pk_add_f32 v[6:7], v[6:7], v[8:9]
	v_pk_add_f32 v[8:9], v[2:3], v[10:11]
	v_pk_add_f32 v[2:3], v[0:1], v[16:17]
	v_pk_add_f32 v[4:5], v[4:5], v[14:15]
	s_nop 0
	v_cvt_pk_bf16_f32 v0, v4, v5
	v_cvt_pk_bf16_f32 v1, v6, v7
	v_cvt_pk_bf16_f32 v2, v2, v3
	v_cvt_pk_bf16_f32 v3, v8, v9
	global_store_dwordx4 v[12:13], v[0:3], off
	s_cbranch_vccnz .LBB0_878
	s_andn2_b64 vcc, exec, s[12:13]
	s_cbranch_vccnz .LBB0_877
	s_barrier
	s_branch .LBB0_877
